# SwiGLU epilogue rstd reads: straight-line fast path when the row panel is cached (8 ds_read_b32 without the per-value branch chain); mid-sequence lgkmcnt(0) removed from the three peeled first load se
# speedup vs baseline: 1.0156x; 1.0011x over previous
; template <class Epi, class Sched, bool ALIGN_EPI = false, bool SP2 = false>
; __device__ __forceinline__ void gemm_phase(PG8_LAS unsigned char* lds, const Gemm g, const Sched& S, const Epi& E) {
;     ...
;         if constexpr (Epi::PEEL) {
;             const char* a1 = cA + kstepA; const char* a2 = cA + 2 * kstepA; const char* b2 = cB + 2 * kstepB; const char* a3 = a2 + kstepA; const char* b3 = b2 + kstepB;
;             PG8_ITER(8);
.LBB0_160:
	s_ashr_i32 s55, s54, 31
	s_lshl_b64 s[2:3], s[54:55], 15
	v_readlane_b32 s8, v255, 15
	s_add_u32 s12, s8, s2
	v_readlane_b32 s2, v255, 16
	s_addc_u32 s13, s2, s3
	s_ashr_i32 s49, s48, 31
	s_lshl_b64 s[2:3], s[48:49], 19
	v_readlane_b32 s8, v255, 29
	s_add_u32 s46, s8, s2
	v_readlane_b32 s2, v255, 40
	s_addc_u32 s47, s2, s3
	s_add_u32 s28, s24, 0x800000
	s_addc_u32 s29, s25, 0
	s_add_u32 s42, s24, 0xc00000
	s_addc_u32 s43, s25, 0
	s_add_i32 s55, 0, 0x10000
	s_and_b64 s[2:3], s[30:31], exec
	s_cselect_b32 s27, s13, s25
	s_cselect_b32 s44, s12, s24
	s_add_i32 vcc_hi, 0, 0x14000
	v_add_u32_e32 v142, s55, v97
	v_add_u32_e32 v143, vcc_hi, v97
	ds_read_b128 v[0:3], v142
	ds_read_b128 v[4:7], v142 offset:1024
	ds_read_b128 v[8:11], v142 offset:2048
	ds_read_b128 v[12:15], v142 offset:3072
	ds_read_b128 v[16:19], v143
	ds_read_b128 v[20:23], v143 offset:1024
	ds_read_b128 v[24:27], v143 offset:2048
	ds_read_b128 v[28:31], v143 offset:3072
	v_writelane_b32 v255, s30, 33
	s_and_b64 s[2:3], s[30:31], exec
	s_cselect_b32 s45, s47, s1
	v_writelane_b32 v255, s31, 34
	s_cselect_b32 s49, s46, s0
	s_add_u32 s2, s24, 0x404000
	s_addc_u32 s3, s25, 0
	s_add_i32 s50, s22, 0xc000
	s_mov_b32 m0, s50
	s_add_i32 s51, s22, 0xe000
	ds_read_b128 v[32:35], v161
	ds_read_b128 v[36:39], v161 offset:1024
	ds_read_b128 v[40:43], v161 offset:2048
	ds_read_b128 v[44:47], v161 offset:3072
	ds_read_b128 v[48:51], v161 offset:4096
	ds_read_b128 v[52:55], v161 offset:5120
	ds_read_b128 v[56:59], v161 offset:6144
	ds_read_b128 v[60:63], v161 offset:7168
	global_load_lds_dwordx4 v130, s[2:3]
	s_mov_b32 m0, s51
	s_nop 0
	global_load_lds_dwordx4 v134, s[2:3]
	s_waitcnt vmcnt(8)
	s_waitcnt lgkmcnt(0)
	s_barrier
	v_mfma_f32_16x16x32_bf16 v[64:67], v[0:3], v[32:35], 0
	v_mfma_f32_16x16x32_bf16 v[68:71], v[8:11], v[32:35], 0
	v_mfma_f32_16x16x32_bf16 v[72:75], v[0:3], v[40:43], 0
	v_mfma_f32_16x16x32_bf16 v[76:79], v[8:11], v[40:43], 0
	v_mfma_f32_16x16x32_bf16 v[80:83], v[0:3], v[48:51], 0
	v_mfma_f32_16x16x32_bf16 v[84:87], v[8:11], v[48:51], 0
	v_mfma_f32_16x16x32_bf16 v[88:91], v[0:3], v[56:59], 0
	v_mfma_f32_16x16x32_bf16 v[92:95], v[8:11], v[56:59], 0
	v_mfma_f32_16x16x32_bf16 v[64:67], v[4:7], v[36:39], v[64:67]
	v_mfma_f32_16x16x32_bf16 v[68:71], v[12:15], v[36:39], v[68:71]
	v_mfma_f32_16x16x32_bf16 v[72:75], v[4:7], v[44:47], v[72:75]
	v_mfma_f32_16x16x32_bf16 v[76:79], v[12:15], v[44:47], v[76:79]
	v_mfma_f32_16x16x32_bf16 v[80:83], v[4:7], v[52:55], v[80:83]
	v_mfma_f32_16x16x32_bf16 v[84:87], v[12:15], v[52:55], v[84:87]
	v_mfma_f32_16x16x32_bf16 v[88:91], v[4:7], v[60:63], v[88:91]
	v_mfma_f32_16x16x32_bf16 v[98:101], v[12:15], v[60:63], v[92:95]
	v_mfma_f32_16x16x32_bf16 v[92:95], v[16:19], v[32:35], 0
	v_mfma_f32_16x16x32_bf16 v[32:35], v[24:27], v[32:35], 0
	v_mfma_f32_16x16x32_bf16 v[106:109], v[20:23], v[36:39], v[92:95]
	v_mfma_f32_16x16x32_bf16 v[32:35], v[28:31], v[36:39], v[32:35]
	v_mfma_f32_16x16x32_bf16 v[36:39], v[16:19], v[40:43], 0
	v_mfma_f32_16x16x32_bf16 v[40:43], v[24:27], v[40:43], 0
	v_mfma_f32_16x16x32_bf16 v[36:39], v[20:23], v[44:47], v[36:39]
	v_mfma_f32_16x16x32_bf16 v[40:43], v[28:31], v[44:47], v[40:43]
	v_mfma_f32_16x16x32_bf16 v[44:47], v[16:19], v[48:51], 0
	v_mfma_f32_16x16x32_bf16 v[48:51], v[24:27], v[48:51], 0
	v_mfma_f32_16x16x32_bf16 v[44:47], v[20:23], v[52:55], v[44:47]
	v_mfma_f32_16x16x32_bf16 v[48:51], v[28:31], v[52:55], v[48:51]
	v_mfma_f32_16x16x32_bf16 v[52:55], v[16:19], v[56:59], 0
	v_mfma_f32_16x16x32_bf16 v[56:59], v[24:27], v[56:59], 0
	v_mfma_f32_16x16x32_bf16 v[52:55], v[20:23], v[60:63], v[52:55]
	v_mfma_f32_16x16x32_bf16 v[56:59], v[28:31], v[60:63], v[56:59]
	s_barrier
	v_lshl_add_u64 v[158:159], s[0:1], 0, v[132:133]
	s_mov_b64 s[2:3], 0x100
	s_add_i32 s55, s55, s10
	v_lshl_add_u64 v[144:145], v[158:159], 0, s[2:3]
	s_mov_b32 m0, s55
	v_lshl_add_u64 v[178:179], s[0:1], 0, v[136:137]
	s_add_i32 vcc_lo, s55, 0x2000
	ds_read_b128 v[60:63], v161 offset:16384
	ds_read_b128 v[92:95], v161 offset:17408
	ds_read_b128 v[102:105], v161 offset:18432
	ds_read_b128 v[110:113], v161 offset:19456
	ds_read_b128 v[114:117], v161 offset:20480
	ds_read_b128 v[118:121], v161 offset:21504
	ds_read_b128 v[122:125], v161 offset:22528
	ds_read_b128 v[126:129], v161 offset:23552
	global_load_lds_dwordx4 v[144:145], off
	v_lshl_add_u64 v[144:145], v[178:179], 0, s[2:3]
	s_add_u32 s2, s0, 0x40100
	s_mov_b32 m0, vcc_lo
	s_addc_u32 s3, s1, 0
	s_add_i32 vcc_hi, vcc_hi, s10
	global_load_lds_dwordx4 v[144:145], off
	s_mov_b32 m0, vcc_hi
	s_add_i32 s56, vcc_hi, 0x2000
	global_load_lds_dwordx4 v132, s[2:3]
	s_mov_b32 m0, s56
	s_nop 0
	global_load_lds_dwordx4 v136, s[2:3]
	s_mov_b32 m0, s22
	s_nop 0
	global_load_lds_dwordx4 v130, s[28:29]
	s_mov_b32 m0, s23
	s_nop 0
	global_load_lds_dwordx4 v134, s[28:29]
	s_waitcnt vmcnt(8)
	s_waitcnt lgkmcnt(0)
	s_barrier
	v_mfma_f32_16x16x32_bf16 v[144:147], v[0:3], v[60:63], 0
	v_mfma_f32_16x16x32_bf16 v[154:157], v[0:3], v[102:105], 0
	v_mfma_f32_16x16x32_bf16 v[166:169], v[0:3], v[114:117], 0
	v_mfma_f32_16x16x32_bf16 v[0:3], v[0:3], v[122:125], 0
	v_mfma_f32_16x16x32_bf16 v[146:149], v[4:7], v[92:95], v[144:147]
	v_mfma_f32_16x16x32_bf16 v[154:157], v[4:7], v[110:113], v[154:157]
	v_mfma_f32_16x16x32_bf16 v[166:169], v[4:7], v[118:121], v[166:169]
	v_mfma_f32_16x16x32_bf16 v[0:3], v[4:7], v[126:129], v[0:3]
	v_mfma_f32_16x16x32_bf16 v[4:7], v[8:11], v[122:125], 0
	v_mfma_f32_16x16x32_bf16 v[150:153], v[8:11], v[60:63], 0
	v_mfma_f32_16x16x32_bf16 v[162:165], v[8:11], v[102:105], 0
	v_mfma_f32_16x16x32_bf16 v[170:173], v[8:11], v[114:117], 0
	v_mfma_f32_16x16x32_bf16 v[4:7], v[12:15], v[126:129], v[4:7]
	v_mfma_f32_16x16x32_bf16 v[150:153], v[12:15], v[92:95], v[150:153]
	v_mfma_f32_16x16x32_bf16 v[162:165], v[12:15], v[110:113], v[162:165]
	v_mfma_f32_16x16x32_bf16 v[170:173], v[12:15], v[118:121], v[170:173]
	v_mfma_f32_16x16x32_bf16 v[12:15], v[24:27], v[60:63], 0
	v_mfma_f32_16x16x32_bf16 v[174:177], v[28:31], v[92:95], v[12:15]
	v_mfma_f32_16x16x32_bf16 v[12:15], v[16:19], v[102:105], 0
	v_mfma_f32_16x16x32_bf16 v[180:183], v[20:23], v[110:113], v[12:15]
	v_mfma_f32_16x16x32_bf16 v[12:15], v[24:27], v[102:105], 0
	v_mfma_f32_16x16x32_bf16 v[184:187], v[28:31], v[110:113], v[12:15]
	v_mfma_f32_16x16x32_bf16 v[12:15], v[16:19], v[114:117], 0
	v_mfma_f32_16x16x32_bf16 v[188:191], v[20:23], v[118:121], v[12:15]
	v_mfma_f32_16x16x32_bf16 v[12:15], v[24:27], v[114:117], 0
	v_mfma_f32_16x16x32_bf16 v[8:11], v[16:19], v[60:63], 0
	v_mfma_f32_16x16x32_bf16 v[192:195], v[28:31], v[118:121], v[12:15]
	v_mfma_f32_16x16x32_bf16 v[12:15], v[16:19], v[122:125], 0
	v_mfma_f32_16x16x32_bf16 v[8:11], v[20:23], v[92:95], v[8:11]
	v_mfma_f32_16x16x32_bf16 v[196:199], v[20:23], v[126:129], v[12:15]
	v_mfma_f32_16x16x32_bf16 v[12:15], v[24:27], v[122:125], 0
	v_mfma_f32_16x16x32_bf16 v[200:203], v[28:31], v[126:129], v[12:15]
	s_barrier
	s_add_i32 s30, 0, 0x18000
	s_add_i32 s57, 0, 0x1c000
	v_add_u32_e32 v144, s30, v97
	v_add_u32_e32 v145, s57, v97
	s_nop 0
	ds_read_b128 v[12:15], v144
	ds_read_b128 v[16:19], v144 offset:1024
	ds_read_b128 v[24:27], v144 offset:2048
	ds_read_b128 v[204:207], v144 offset:3072
	ds_read_b128 v[208:211], v145
	ds_read_b128 v[212:215], v145 offset:1024
	ds_read_b128 v[216:219], v145 offset:2048
	ds_read_b128 v[220:223], v145 offset:3072
	s_add_u32 s2, s24, 0x804000
	s_addc_u32 s3, s25, 0
	s_mov_b32 m0, s39
	ds_read_b128 v[20:23], v161 offset:32768
	ds_read_b128 v[28:31], v161 offset:33792
	ds_read_b128 v[60:63], v161 offset:34816
	ds_read_b128 v[224:227], v161 offset:35840
	ds_read_b128 v[228:231], v161 offset:36864
	ds_read_b128 v[234:237], v161 offset:37888
	ds_read_b128 v[238:241], v161 offset:38912
	ds_read_b128 v[242:245], v161 offset:39936
	global_load_lds_dwordx4 v130, s[2:3]
	s_mov_b32 m0, s52
	s_nop 0
	global_load_lds_dwordx4 v134, s[2:3]
	s_waitcnt vmcnt(8)
	s_waitcnt lgkmcnt(0)
	s_barrier
	v_mfma_f32_16x16x32_bf16 v[64:67], v[12:15], v[20:23], v[64:67]
	v_mfma_f32_16x16x32_bf16 v[126:129], v[16:19], v[28:31], v[64:67]
	v_mfma_f32_16x16x32_bf16 v[64:67], v[24:27], v[20:23], v[68:71]
	v_mfma_f32_16x16x32_bf16 v[118:121], v[204:207], v[28:31], v[64:67]
	v_mfma_f32_16x16x32_bf16 v[64:67], v[12:15], v[60:63], v[72:75]
	v_mfma_f32_16x16x32_bf16 v[110:113], v[16:19], v[224:227], v[64:67]
	v_mfma_f32_16x16x32_bf16 v[64:67], v[24:27], v[60:63], v[76:79]
	v_mfma_f32_16x16x32_bf16 v[102:105], v[204:207], v[224:227], v[64:67]
	v_mfma_f32_16x16x32_bf16 v[64:67], v[12:15], v[228:231], v[80:83]
	v_mfma_f32_16x16x32_bf16 v[92:95], v[16:19], v[234:237], v[64:67]
	v_mfma_f32_16x16x32_bf16 v[64:67], v[24:27], v[228:231], v[84:87]
	v_mfma_f32_16x16x32_bf16 v[84:87], v[204:207], v[234:237], v[64:67]
	v_mfma_f32_16x16x32_bf16 v[64:67], v[12:15], v[238:241], v[88:91]
	v_mfma_f32_16x16x32_bf16 v[76:79], v[16:19], v[242:245], v[64:67]
	v_mfma_f32_16x16x32_bf16 v[64:67], v[24:27], v[238:241], v[98:101]
	v_mfma_f32_16x16x32_bf16 v[68:71], v[204:207], v[242:245], v[64:67]
	v_mfma_f32_16x16x32_bf16 v[64:67], v[208:211], v[20:23], v[106:109]
	v_mfma_f32_16x16x32_bf16 v[20:23], v[216:219], v[20:23], v[32:35]
	v_mfma_f32_16x16x32_bf16 v[114:117], v[220:223], v[28:31], v[20:23]
	v_mfma_f32_16x16x32_bf16 v[20:23], v[208:211], v[60:63], v[36:39]
	v_mfma_f32_16x16x32_bf16 v[106:109], v[212:215], v[224:227], v[20:23]
	v_mfma_f32_16x16x32_bf16 v[20:23], v[216:219], v[60:63], v[40:43]
	v_mfma_f32_16x16x32_bf16 v[98:101], v[220:223], v[224:227], v[20:23]
	v_mfma_f32_16x16x32_bf16 v[20:23], v[208:211], v[228:231], v[44:47]
	v_mfma_f32_16x16x32_bf16 v[88:91], v[212:215], v[234:237], v[20:23]
	v_mfma_f32_16x16x32_bf16 v[20:23], v[216:219], v[228:231], v[48:51]
	v_mfma_f32_16x16x32_bf16 v[80:83], v[220:223], v[234:237], v[20:23]
	v_mfma_f32_16x16x32_bf16 v[20:23], v[208:211], v[238:241], v[52:55]
	v_mfma_f32_16x16x32_bf16 v[72:75], v[212:215], v[242:245], v[20:23]
	v_mfma_f32_16x16x32_bf16 v[20:23], v[216:219], v[238:241], v[56:59]
	v_mfma_f32_16x16x32_bf16 v[122:125], v[212:215], v[28:31], v[64:67]
	v_mfma_f32_16x16x32_bf16 v[64:67], v[220:223], v[242:245], v[20:23]
	s_barrier
; template <class Epi, class Sched, bool ALIGN_EPI = false, bool SP2 = false>
; __device__ __forceinline__ void gemm_phase(PG8_LAS unsigned char* lds, const Gemm g, const Sched& S, const Epi& E) {
;     ...
;         if constexpr (Epi::PEEL) {
;             const char* a1 = cA + kstepA; const char* a2 = cA + 2 * kstepA; const char* b2 = cB + 2 * kstepB; const char* a3 = a2 + kstepA; const char* b3 = b2 + kstepB;
;             PG8_ITER(8);
;         }
;         for (int t = (Epi::PEEL ? 2 : 0); t < nt; t += 2) {
	s_mov_b64 s[2:3], 0x180
	s_add_i32 s30, s30, s10
	s_nop 1
	v_lshl_add_u64 v[20:21], v[158:159], 0, s[2:3]
	s_mov_b32 m0, s30
	s_add_i32 s31, s30, 0x2000
	ds_read_b128 v[32:35], v161 offset:49152
	ds_read_b128 v[40:43], v161 offset:50176
	ds_read_b128 v[224:227], v161 offset:51200
	ds_read_b128 v[228:231], v161 offset:52224
	ds_read_b128 v[234:237], v161 offset:53248
	ds_read_b128 v[238:241], v161 offset:54272
	ds_read_b128 v[242:245], v161 offset:55296
	ds_read_b128 v[246:249], v161 offset:56320
	global_load_lds_dwordx4 v[20:21], off
	v_lshl_add_u64 v[20:21], v[178:179], 0, s[2:3]
	s_add_u32 s2, s0, 0x40180
	s_mov_b32 m0, s31
	s_addc_u32 s3, s1, 0
	s_add_i32 s57, s57, s10
	global_load_lds_dwordx4 v[20:21], off
	s_mov_b32 m0, s57
	s_add_i32 s96, s57, 0x2000
	global_load_lds_dwordx4 v132, s[2:3]
	s_mov_b32 m0, s96
	s_nop 0
	global_load_lds_dwordx4 v136, s[2:3]
	s_mov_b32 m0, s11
	s_nop 0
	global_load_lds_dwordx4 v130, s[42:43]
	s_mov_b32 m0, s19
	s_nop 0
	global_load_lds_dwordx4 v134, s[42:43]
	s_waitcnt vmcnt(8)
	s_waitcnt lgkmcnt(0)
	s_barrier
	v_mfma_f32_16x16x32_bf16 v[20:23], v[12:15], v[32:35], v[146:149]
	v_mfma_f32_16x16x32_bf16 v[60:63], v[16:19], v[40:43], v[20:23]
	v_mfma_f32_16x16x32_bf16 v[20:23], v[24:27], v[32:35], v[150:153]
	v_mfma_f32_16x16x32_bf16 v[52:55], v[204:207], v[40:43], v[20:23]
	v_mfma_f32_16x16x32_bf16 v[20:23], v[12:15], v[224:227], v[154:157]
	v_mfma_f32_16x16x32_bf16 v[44:47], v[16:19], v[228:231], v[20:23]
	v_mfma_f32_16x16x32_bf16 v[20:23], v[24:27], v[224:227], v[162:165]
	v_mfma_f32_16x16x32_bf16 v[36:39], v[204:207], v[228:231], v[20:23]
	v_mfma_f32_16x16x32_bf16 v[20:23], v[12:15], v[234:237], v[166:169]
	v_mfma_f32_16x16x32_bf16 v[0:3], v[12:15], v[242:245], v[0:3]
	v_mfma_f32_16x16x32_bf16 v[28:31], v[16:19], v[238:241], v[20:23]
	v_mfma_f32_16x16x32_bf16 v[20:23], v[24:27], v[234:237], v[170:173]
	v_mfma_f32_16x16x32_bf16 v[12:15], v[16:19], v[246:249], v[0:3]
	v_mfma_f32_16x16x32_bf16 v[0:3], v[24:27], v[242:245], v[4:7]
	v_mfma_f32_16x16x32_bf16 v[20:23], v[204:207], v[238:241], v[20:23]
	v_mfma_f32_16x16x32_bf16 v[4:7], v[204:207], v[246:249], v[0:3]
	v_mfma_f32_16x16x32_bf16 v[0:3], v[208:211], v[32:35], v[8:11]
	v_mfma_f32_16x16x32_bf16 v[56:59], v[212:215], v[40:43], v[0:3]
	v_mfma_f32_16x16x32_bf16 v[0:3], v[216:219], v[32:35], v[174:177]
	v_mfma_f32_16x16x32_bf16 v[48:51], v[220:223], v[40:43], v[0:3]
	v_mfma_f32_16x16x32_bf16 v[0:3], v[208:211], v[224:227], v[180:183]
	v_mfma_f32_16x16x32_bf16 v[40:43], v[212:215], v[228:231], v[0:3]
	v_mfma_f32_16x16x32_bf16 v[0:3], v[216:219], v[224:227], v[184:187]
	v_mfma_f32_16x16x32_bf16 v[32:35], v[220:223], v[228:231], v[0:3]
	v_mfma_f32_16x16x32_bf16 v[0:3], v[208:211], v[234:237], v[188:191]
	v_mfma_f32_16x16x32_bf16 v[24:27], v[212:215], v[238:241], v[0:3]
	v_mfma_f32_16x16x32_bf16 v[0:3], v[216:219], v[234:237], v[192:195]
	v_mfma_f32_16x16x32_bf16 v[16:19], v[220:223], v[238:241], v[0:3]
	v_mfma_f32_16x16x32_bf16 v[0:3], v[208:211], v[242:245], v[196:199]
	v_mfma_f32_16x16x32_bf16 v[8:11], v[212:215], v[246:249], v[0:3]
	v_mfma_f32_16x16x32_bf16 v[0:3], v[216:219], v[242:245], v[200:203]
	v_mfma_f32_16x16x32_bf16 v[0:3], v[220:223], v[246:249], v[0:3]
	s_barrier
	s_add_u32 s3, s0, 0x200
	s_addc_u32 s2, s1, 0
	s_add_u32 s0, s24, 0xc04000
	s_addc_u32 s1, s25, 0
	s_mov_b32 s18, 0

; template <class Epi, class Sched, bool ALIGN_EPI = false, bool SP2 = false>
; __device__ __forceinline__ void gemm_phase(PG8_LAS unsigned char* lds, const Gemm g, const Sched& S, const Epi& E) {
;     ...
;         if constexpr (Epi::PEEL) {
;             const char* a1 = cA + kstepA; const char* a2 = cA + 2 * kstepA; const char* b2 = cB + 2 * kstepB; const char* a3 = a2 + kstepA; const char* b3 = b2 + kstepB;
;             PG8_ITER(8);
.LBB0_249:
	s_ashr_i32 s49, s48, 31
	s_lshl_b64 s[2:3], s[48:49], 15
	v_readlane_b32 s11, v255, 15
	s_add_u32 s50, s11, s2
	v_readlane_b32 s2, v255, 16
	s_addc_u32 s51, s2, s3
	s_ashr_i32 s47, s46, 31
	s_lshl_b64 s[2:3], s[46:47], 19
	s_add_u32 s52, s38, s2
	s_addc_u32 s53, s19, s3
	s_add_u32 s28, s42, 0x800000
	s_addc_u32 s29, s43, 0
	s_add_u32 s44, s42, 0xc00000
	s_addc_u32 s45, s43, 0
	s_add_i32 s99, 0, 0x10000
	s_and_b64 s[2:3], s[40:41], exec
	s_cselect_b32 s27, s51, s43
	s_cselect_b32 s47, s50, s42
	s_add_i32 vcc_hi, 0, 0x14000
	v_add_u32_e32 v130, s99, v97
	v_add_u32_e32 v131, vcc_hi, v97
	ds_read_b128 v[0:3], v130
	ds_read_b128 v[4:7], v130 offset:1024
	ds_read_b128 v[8:11], v130 offset:2048
	ds_read_b128 v[12:15], v130 offset:3072
	ds_read_b128 v[16:19], v131
	ds_read_b128 v[20:23], v131 offset:1024
	ds_read_b128 v[24:27], v131 offset:2048
	ds_read_b128 v[28:31], v131 offset:3072
	s_and_b64 s[2:3], s[40:41], exec
	s_cselect_b32 s49, s53, s25
	s_cselect_b32 s54, s52, s24
	s_add_u32 s2, s42, 0x404000
	s_addc_u32 s3, s43, 0
	s_add_i32 s55, s22, 0xc000
	s_mov_b32 m0, s55
	s_add_i32 s98, s22, 0xe000
	ds_read_b128 v[32:35], v151
	ds_read_b128 v[36:39], v151 offset:1024
	ds_read_b128 v[40:43], v151 offset:2048
	ds_read_b128 v[44:47], v151 offset:3072
	ds_read_b128 v[48:51], v151 offset:4096
	ds_read_b128 v[52:55], v151 offset:5120
	ds_read_b128 v[56:59], v151 offset:6144
	ds_read_b128 v[60:63], v151 offset:7168
	global_load_lds_dwordx4 v134, s[2:3]
	s_mov_b32 m0, s98
	s_nop 0
	global_load_lds_dwordx4 v138, s[2:3]
	s_waitcnt vmcnt(8)
	s_waitcnt lgkmcnt(0)
	s_barrier
	v_mfma_f32_16x16x32_bf16 v[84:87], v[8:11], v[48:51], 0
	v_mfma_f32_16x16x32_bf16 v[88:91], v[12:15], v[52:55], v[84:87]
	v_mfma_f32_16x16x32_bf16 v[84:87], v[0:3], v[56:59], 0
	v_mfma_f32_16x16x32_bf16 v[64:67], v[0:3], v[32:35], 0
	v_mfma_f32_16x16x32_bf16 v[68:71], v[8:11], v[32:35], 0
	v_mfma_f32_16x16x32_bf16 v[72:75], v[0:3], v[40:43], 0
	v_mfma_f32_16x16x32_bf16 v[76:79], v[8:11], v[40:43], 0
	v_mfma_f32_16x16x32_bf16 v[80:83], v[0:3], v[48:51], 0
	v_mfma_f32_16x16x32_bf16 v[92:95], v[4:7], v[60:63], v[84:87]
	v_mfma_f32_16x16x32_bf16 v[84:87], v[8:11], v[56:59], 0
	v_mfma_f32_16x16x32_bf16 v[64:67], v[4:7], v[36:39], v[64:67]
	v_mfma_f32_16x16x32_bf16 v[68:71], v[12:15], v[36:39], v[68:71]
	v_mfma_f32_16x16x32_bf16 v[72:75], v[4:7], v[44:47], v[72:75]
	v_mfma_f32_16x16x32_bf16 v[76:79], v[12:15], v[44:47], v[76:79]
	v_mfma_f32_16x16x32_bf16 v[80:83], v[4:7], v[52:55], v[80:83]
	v_mfma_f32_16x16x32_bf16 v[106:109], v[12:15], v[60:63], v[84:87]
	v_mfma_f32_16x16x32_bf16 v[84:87], v[16:19], v[32:35], 0
	v_mfma_f32_16x16x32_bf16 v[32:35], v[24:27], v[32:35], 0
	v_mfma_f32_16x16x32_bf16 v[110:113], v[20:23], v[36:39], v[84:87]
	v_mfma_f32_16x16x32_bf16 v[32:35], v[28:31], v[36:39], v[32:35]
	v_mfma_f32_16x16x32_bf16 v[36:39], v[16:19], v[40:43], 0
	v_mfma_f32_16x16x32_bf16 v[40:43], v[24:27], v[40:43], 0
	v_mfma_f32_16x16x32_bf16 v[36:39], v[20:23], v[44:47], v[36:39]
	v_mfma_f32_16x16x32_bf16 v[40:43], v[28:31], v[44:47], v[40:43]
	v_mfma_f32_16x16x32_bf16 v[44:47], v[16:19], v[48:51], 0
	v_mfma_f32_16x16x32_bf16 v[48:51], v[24:27], v[48:51], 0
	v_mfma_f32_16x16x32_bf16 v[44:47], v[20:23], v[52:55], v[44:47]
	v_mfma_f32_16x16x32_bf16 v[48:51], v[28:31], v[52:55], v[48:51]
	v_mfma_f32_16x16x32_bf16 v[52:55], v[16:19], v[56:59], 0
	v_mfma_f32_16x16x32_bf16 v[56:59], v[24:27], v[56:59], 0
	v_mfma_f32_16x16x32_bf16 v[52:55], v[20:23], v[60:63], v[52:55]
	v_mfma_f32_16x16x32_bf16 v[56:59], v[28:31], v[60:63], v[56:59]
	s_barrier
	v_lshl_add_u64 v[176:177], s[24:25], 0, v[136:137]
	s_mov_b64 s[2:3], 0x100
	s_add_i32 s99, s99, s10
	v_lshl_add_u64 v[132:133], v[176:177], 0, s[2:3]
	s_mov_b32 m0, s99
	v_lshl_add_u64 v[178:179], s[24:25], 0, v[140:141]
	s_add_i32 vcc_lo, s99, 0x2000
	ds_read_b128 v[60:63], v151 offset:16384
	ds_read_b128 v[84:87], v151 offset:17408
	ds_read_b128 v[98:101], v151 offset:18432
	ds_read_b128 v[102:105], v151 offset:19456
	ds_read_b128 v[114:117], v151 offset:20480
	ds_read_b128 v[118:121], v151 offset:21504
	ds_read_b128 v[122:125], v151 offset:22528
	ds_read_b128 v[126:129], v151 offset:23552
	global_load_lds_dwordx4 v[132:133], off
	v_lshl_add_u64 v[132:133], v[178:179], 0, s[2:3]
	s_add_u32 s2, s24, 0x40100
	s_mov_b32 m0, vcc_lo
	s_addc_u32 s3, s25, 0
	s_add_i32 vcc_hi, vcc_hi, s10
	global_load_lds_dwordx4 v[132:133], off
	s_mov_b32 m0, vcc_hi
	s_add_i32 s30, vcc_hi, 0x2000
	global_load_lds_dwordx4 v136, s[2:3]
	s_mov_b32 m0, s30
	s_mov_b64 s[34:35], 0x100
	global_load_lds_dwordx4 v140, s[2:3]
	s_mov_b32 m0, s22
	s_nop 0
	global_load_lds_dwordx4 v134, s[28:29]
	s_mov_b32 m0, s23
	s_nop 0
	global_load_lds_dwordx4 v138, s[28:29]
	s_waitcnt vmcnt(8)
	s_waitcnt lgkmcnt(0)
	s_barrier
	v_mfma_f32_16x16x32_bf16 v[146:149], v[0:3], v[60:63], 0
	v_mfma_f32_16x16x32_bf16 v[156:159], v[0:3], v[98:101], 0
	v_mfma_f32_16x16x32_bf16 v[164:167], v[0:3], v[114:117], 0
	v_mfma_f32_16x16x32_bf16 v[0:3], v[0:3], v[122:125], 0
	v_mfma_f32_16x16x32_bf16 v[146:149], v[4:7], v[84:87], v[146:149]
	v_mfma_f32_16x16x32_bf16 v[156:159], v[4:7], v[102:105], v[156:159]
	v_mfma_f32_16x16x32_bf16 v[164:167], v[4:7], v[118:121], v[164:167]
	v_mfma_f32_16x16x32_bf16 v[0:3], v[4:7], v[126:129], v[0:3]
	v_mfma_f32_16x16x32_bf16 v[4:7], v[8:11], v[122:125], 0
	v_mfma_f32_16x16x32_bf16 v[152:155], v[8:11], v[60:63], 0
	v_mfma_f32_16x16x32_bf16 v[160:163], v[8:11], v[98:101], 0
	v_mfma_f32_16x16x32_bf16 v[168:171], v[8:11], v[114:117], 0
	v_mfma_f32_16x16x32_bf16 v[8:11], v[12:15], v[126:129], v[4:7]
	v_mfma_f32_16x16x32_bf16 v[152:155], v[12:15], v[84:87], v[152:155]
	v_mfma_f32_16x16x32_bf16 v[160:163], v[12:15], v[102:105], v[160:163]
	v_mfma_f32_16x16x32_bf16 v[168:171], v[12:15], v[118:121], v[168:171]
	v_mfma_f32_16x16x32_bf16 v[4:7], v[16:19], v[60:63], 0
	v_mfma_f32_16x16x32_bf16 v[12:15], v[20:23], v[84:87], v[4:7]
	v_mfma_f32_16x16x32_bf16 v[4:7], v[24:27], v[60:63], 0
	v_mfma_f32_16x16x32_bf16 v[172:175], v[28:31], v[84:87], v[4:7]
	v_mfma_f32_16x16x32_bf16 v[4:7], v[16:19], v[98:101], 0
	v_mfma_f32_16x16x32_bf16 v[180:183], v[20:23], v[102:105], v[4:7]
	v_mfma_f32_16x16x32_bf16 v[4:7], v[24:27], v[98:101], 0
	v_mfma_f32_16x16x32_bf16 v[184:187], v[28:31], v[102:105], v[4:7]
	v_mfma_f32_16x16x32_bf16 v[4:7], v[16:19], v[114:117], 0
	v_mfma_f32_16x16x32_bf16 v[188:191], v[20:23], v[118:121], v[4:7]
	v_mfma_f32_16x16x32_bf16 v[4:7], v[24:27], v[114:117], 0
	v_mfma_f32_16x16x32_bf16 v[192:195], v[28:31], v[118:121], v[4:7]
	v_mfma_f32_16x16x32_bf16 v[4:7], v[16:19], v[122:125], 0
	v_mfma_f32_16x16x32_bf16 v[196:199], v[20:23], v[126:129], v[4:7]
	v_mfma_f32_16x16x32_bf16 v[4:7], v[24:27], v[122:125], 0
	v_mfma_f32_16x16x32_bf16 v[200:203], v[28:31], v[126:129], v[4:7]
	s_barrier
	s_add_i32 s31, 0, 0x18000
	s_add_i32 s13, 0, 0x1c000
	v_add_u32_e32 v132, s31, v97
	v_add_u32_e32 v133, s13, v97
	s_nop 0
	ds_read_b128 v[4:7], v132
	ds_read_b128 v[24:27], v132 offset:1024
	ds_read_b128 v[28:31], v132 offset:2048
	ds_read_b128 v[60:63], v132 offset:3072
	ds_read_b128 v[204:207], v133
	ds_read_b128 v[208:211], v133 offset:1024
	ds_read_b128 v[212:215], v133 offset:2048
	ds_read_b128 v[216:219], v133 offset:3072
	s_add_u32 s2, s42, 0x804000
	s_addc_u32 s3, s43, 0
	s_mov_b32 m0, s39
	ds_read_b128 v[16:19], v151 offset:32768
	ds_read_b128 v[20:23], v151 offset:33792
	ds_read_b128 v[220:223], v151 offset:34816
	ds_read_b128 v[224:227], v151 offset:35840
	ds_read_b128 v[228:231], v151 offset:36864
	ds_read_b128 v[234:237], v151 offset:37888
	ds_read_b128 v[238:241], v151 offset:38912
	ds_read_b128 v[242:245], v151 offset:39936
	global_load_lds_dwordx4 v134, s[2:3]
	s_mov_b32 m0, s56
	s_nop 0
	global_load_lds_dwordx4 v138, s[2:3]
	s_waitcnt vmcnt(8)
	s_waitcnt lgkmcnt(0)
	s_barrier
	v_mfma_f32_16x16x32_bf16 v[64:67], v[4:7], v[16:19], v[64:67]
	v_mfma_f32_16x16x32_bf16 v[118:121], v[24:27], v[20:23], v[64:67]
	v_mfma_f32_16x16x32_bf16 v[64:67], v[28:31], v[16:19], v[68:71]
	v_mfma_f32_16x16x32_bf16 v[114:117], v[60:63], v[20:23], v[64:67]
	v_mfma_f32_16x16x32_bf16 v[64:67], v[4:7], v[220:223], v[72:75]
	v_mfma_f32_16x16x32_bf16 v[102:105], v[24:27], v[224:227], v[64:67]
	v_mfma_f32_16x16x32_bf16 v[64:67], v[28:31], v[220:223], v[76:79]
	v_mfma_f32_16x16x32_bf16 v[98:101], v[60:63], v[224:227], v[64:67]
	v_mfma_f32_16x16x32_bf16 v[64:67], v[4:7], v[228:231], v[80:83]
	v_mfma_f32_16x16x32_bf16 v[84:87], v[24:27], v[234:237], v[64:67]
	v_mfma_f32_16x16x32_bf16 v[64:67], v[28:31], v[228:231], v[88:91]
	v_mfma_f32_16x16x32_bf16 v[80:83], v[60:63], v[234:237], v[64:67]
	v_mfma_f32_16x16x32_bf16 v[64:67], v[4:7], v[238:241], v[92:95]
	v_mfma_f32_16x16x32_bf16 v[68:71], v[24:27], v[242:245], v[64:67]
	v_mfma_f32_16x16x32_bf16 v[64:67], v[28:31], v[238:241], v[106:109]
	v_mfma_f32_16x16x32_bf16 v[64:67], v[60:63], v[242:245], v[64:67]
	v_mfma_f32_16x16x32_bf16 v[72:75], v[204:207], v[16:19], v[110:113]
	v_mfma_f32_16x16x32_bf16 v[16:19], v[212:215], v[16:19], v[32:35]
	v_mfma_f32_16x16x32_bf16 v[122:125], v[216:219], v[20:23], v[16:19]
	v_mfma_f32_16x16x32_bf16 v[16:19], v[204:207], v[220:223], v[36:39]
	v_mfma_f32_16x16x32_bf16 v[110:113], v[208:211], v[224:227], v[16:19]
	v_mfma_f32_16x16x32_bf16 v[16:19], v[212:215], v[220:223], v[40:43]
	v_mfma_f32_16x16x32_bf16 v[106:109], v[216:219], v[224:227], v[16:19]
	v_mfma_f32_16x16x32_bf16 v[16:19], v[204:207], v[228:231], v[44:47]
	v_mfma_f32_16x16x32_bf16 v[92:95], v[208:211], v[234:237], v[16:19]
	v_mfma_f32_16x16x32_bf16 v[16:19], v[212:215], v[228:231], v[48:51]
	v_mfma_f32_16x16x32_bf16 v[88:91], v[216:219], v[234:237], v[16:19]
	v_mfma_f32_16x16x32_bf16 v[16:19], v[204:207], v[238:241], v[52:55]
	v_mfma_f32_16x16x32_bf16 v[76:79], v[208:211], v[242:245], v[16:19]
	v_mfma_f32_16x16x32_bf16 v[16:19], v[212:215], v[238:241], v[56:59]
	v_mfma_f32_16x16x32_bf16 v[126:129], v[208:211], v[20:23], v[72:75]
	v_mfma_f32_16x16x32_bf16 v[72:75], v[216:219], v[242:245], v[16:19]
	s_barrier
; template <class Epi, class Sched, bool ALIGN_EPI = false, bool SP2 = false>
; __device__ __forceinline__ void gemm_phase(PG8_LAS unsigned char* lds, const Gemm g, const Sched& S, const Epi& E) {
;     ...
;         if constexpr (Epi::PEEL) {
;             const char* a1 = cA + kstepA; const char* a2 = cA + 2 * kstepA; const char* b2 = cB + 2 * kstepB; const char* a3 = a2 + kstepA; const char* b3 = b2 + kstepB;
;             PG8_ITER(8);
;         }
;         for (int t = (Epi::PEEL ? 2 : 0); t < nt; t += 2) {
;             const bool last = (t == nt - 2);
;             const char* a1 = cA + (size_t)(t + 1) * kstepA;
;             const char* a2 = last ? nA : cA + (size_t)(t + 2) * kstepA; const char* b2 = last ? nB : cB + (size_t)(t + 2) * kstepB;
;             const char* a3 = a2 + kstepA; const char* b3 = b2 + kstepB;
	s_mov_b64 s[2:3], 0x180
	s_add_i32 s31, s31, s10
	s_nop 1
	v_lshl_add_u64 v[16:17], v[176:177], 0, s[2:3]
	s_mov_b32 m0, s31
	s_add_i32 s12, s31, 0x2000
	ds_read_b128 v[40:43], v151 offset:49152
	ds_read_b128 v[44:47], v151 offset:50176
	ds_read_b128 v[220:223], v151 offset:51200
	ds_read_b128 v[224:227], v151 offset:52224
	ds_read_b128 v[228:231], v151 offset:53248
	ds_read_b128 v[234:237], v151 offset:54272
	ds_read_b128 v[238:241], v151 offset:55296
	ds_read_b128 v[242:245], v151 offset:56320
	global_load_lds_dwordx4 v[16:17], off
	v_lshl_add_u64 v[16:17], v[178:179], 0, s[2:3]
	s_add_u32 s2, s24, 0x40180
	s_mov_b32 m0, s12
	s_addc_u32 s3, s25, 0
	s_add_i32 s13, s13, s10
	global_load_lds_dwordx4 v[16:17], off
	s_mov_b32 m0, s13
	s_add_i32 s11, s13, 0x2000
	global_load_lds_dwordx4 v136, s[2:3]
	s_mov_b32 m0, s11
	s_nop 0
	global_load_lds_dwordx4 v140, s[2:3]
	s_mov_b32 m0, s59
	s_nop 0
	global_load_lds_dwordx4 v134, s[44:45]
	s_mov_b32 m0, s96
	s_nop 0
	global_load_lds_dwordx4 v138, s[44:45]
	s_waitcnt vmcnt(8)
	s_waitcnt lgkmcnt(0)
	s_barrier
	v_mfma_f32_16x16x32_bf16 v[16:19], v[4:7], v[40:43], v[146:149]
	v_mfma_f32_16x16x32_bf16 v[52:55], v[24:27], v[44:47], v[16:19]
	v_mfma_f32_16x16x32_bf16 v[16:19], v[28:31], v[40:43], v[152:155]
	v_mfma_f32_16x16x32_bf16 v[48:51], v[60:63], v[44:47], v[16:19]
	v_mfma_f32_16x16x32_bf16 v[16:19], v[4:7], v[220:223], v[156:159]
	v_mfma_f32_16x16x32_bf16 v[36:39], v[24:27], v[224:227], v[16:19]
	v_mfma_f32_16x16x32_bf16 v[16:19], v[28:31], v[220:223], v[160:163]
	v_mfma_f32_16x16x32_bf16 v[32:35], v[60:63], v[224:227], v[16:19]
	v_mfma_f32_16x16x32_bf16 v[16:19], v[4:7], v[228:231], v[164:167]
	v_mfma_f32_16x16x32_bf16 v[0:3], v[4:7], v[238:241], v[0:3]
	v_mfma_f32_16x16x32_bf16 v[20:23], v[24:27], v[234:237], v[16:19]
	v_mfma_f32_16x16x32_bf16 v[16:19], v[28:31], v[228:231], v[168:171]
	v_mfma_f32_16x16x32_bf16 v[4:7], v[24:27], v[242:245], v[0:3]
	v_mfma_f32_16x16x32_bf16 v[0:3], v[28:31], v[238:241], v[8:11]
	v_mfma_f32_16x16x32_bf16 v[16:19], v[60:63], v[234:237], v[16:19]
	v_mfma_f32_16x16x32_bf16 v[0:3], v[60:63], v[242:245], v[0:3]
	v_mfma_f32_16x16x32_bf16 v[8:11], v[204:207], v[40:43], v[12:15]
	v_mfma_f32_16x16x32_bf16 v[60:63], v[208:211], v[44:47], v[8:11]
	v_mfma_f32_16x16x32_bf16 v[8:11], v[212:215], v[40:43], v[172:175]
	v_mfma_f32_16x16x32_bf16 v[56:59], v[216:219], v[44:47], v[8:11]
	v_mfma_f32_16x16x32_bf16 v[8:11], v[204:207], v[220:223], v[180:183]
	v_mfma_f32_16x16x32_bf16 v[44:47], v[208:211], v[224:227], v[8:11]
	v_mfma_f32_16x16x32_bf16 v[8:11], v[212:215], v[220:223], v[184:187]
	v_mfma_f32_16x16x32_bf16 v[40:43], v[216:219], v[224:227], v[8:11]
	v_mfma_f32_16x16x32_bf16 v[8:11], v[204:207], v[228:231], v[188:191]
	v_mfma_f32_16x16x32_bf16 v[28:31], v[208:211], v[234:237], v[8:11]
	v_mfma_f32_16x16x32_bf16 v[8:11], v[212:215], v[228:231], v[192:195]
	v_mfma_f32_16x16x32_bf16 v[24:27], v[216:219], v[234:237], v[8:11]
	v_mfma_f32_16x16x32_bf16 v[8:11], v[204:207], v[238:241], v[196:199]
	v_mfma_f32_16x16x32_bf16 v[12:15], v[208:211], v[242:245], v[8:11]
	v_mfma_f32_16x16x32_bf16 v[8:11], v[212:215], v[238:241], v[200:203]
	v_mfma_f32_16x16x32_bf16 v[8:11], v[216:219], v[242:245], v[8:11]
	s_barrier
	s_add_u32 s3, s24, 0x200
	s_addc_u32 s2, s25, 0
	s_add_u32 s24, s42, 0xc04000
	s_addc_u32 s25, s43, 0
	s_mov_b32 s18, 0

; template <class Epi, class Sched, bool ALIGN_EPI = false, bool SP2 = false>
; __device__ __forceinline__ void gemm_phase(PG8_LAS unsigned char* lds, const Gemm g, const Sched& S, const Epi& E) {
;     ...
;         const char* nA = has_next ? (const char*)g.A + (size_t)nxt.pm * tstepA : cA; const char* nB = has_next ? (const char*)g.Bt + (size_t)nxt.pn * tstepB : cB;
.LBB0_477:
	s_ashr_i32 s27, s26, 31
	s_lshl_b64 s[2:3], s[26:27], 15
	v_readlane_b32 s10, v255, 15
	s_add_u32 s28, s10, s2
	v_readlane_b32 s2, v255, 16
	s_addc_u32 s29, s2, s3
	s_ashr_i32 s25, s24, 31
	s_lshl_b64 s[2:3], s[24:25], 19
	s_add_u32 s30, s19, s2
	s_addc_u32 s31, s22, s3
	s_add_u32 s44, s34, 0x800000
	s_addc_u32 s45, s35, 0
	s_add_u32 s42, s34, 0xc00000
	s_addc_u32 s43, s35, 0
	s_add_i32 s61, 0, 0x10000
	s_and_b64 s[2:3], s[40:41], exec
	s_cselect_b32 s25, s29, s35
	s_cselect_b32 s27, s28, s34
	s_add_i32 s97, 0, 0x14000
	v_add_u32_e32 v142, s61, v97
	v_add_u32_e32 v143, s97, v97
	ds_read_b128 v[0:3], v142
	ds_read_b128 v[4:7], v142 offset:1024
	ds_read_b128 v[8:11], v142 offset:2048
	ds_read_b128 v[12:15], v142 offset:3072
	ds_read_b128 v[16:19], v143
	ds_read_b128 v[20:23], v143 offset:1024
	ds_read_b128 v[24:27], v143 offset:2048
	ds_read_b128 v[28:31], v143 offset:3072
	s_and_b64 s[2:3], s[40:41], exec
	s_cselect_b32 s57, s31, s1
	s_cselect_b32 s58, s30, s0
	s_add_u32 s2, s34, 0x404000
	s_addc_u32 s3, s35, 0
	s_add_i32 s59, s23, 0xc000
	s_mov_b32 m0, s59
	s_add_i32 s60, s23, 0xe000
	ds_read_b128 v[32:35], v156
	ds_read_b128 v[36:39], v156 offset:1024
	ds_read_b128 v[40:43], v156 offset:2048
	ds_read_b128 v[44:47], v156 offset:3072
	ds_read_b128 v[48:51], v156 offset:4096
	ds_read_b128 v[52:55], v156 offset:5120
	ds_read_b128 v[56:59], v156 offset:6144
	ds_read_b128 v[60:63], v156 offset:7168
	global_load_lds_dwordx4 v130, s[2:3]
	s_mov_b32 m0, s60
	s_nop 0
	global_load_lds_dwordx4 v134, s[2:3]
	s_waitcnt vmcnt(8)
	s_waitcnt lgkmcnt(0)
	s_barrier
	v_mfma_f32_16x16x32_bf16 v[88:91], v[0:3], v[56:59], 0
	v_mfma_f32_16x16x32_bf16 v[64:67], v[0:3], v[32:35], 0
	v_mfma_f32_16x16x32_bf16 v[68:71], v[8:11], v[32:35], 0
	v_mfma_f32_16x16x32_bf16 v[72:75], v[0:3], v[40:43], 0
	v_mfma_f32_16x16x32_bf16 v[76:79], v[8:11], v[40:43], 0
	v_mfma_f32_16x16x32_bf16 v[80:83], v[0:3], v[48:51], 0
	v_mfma_f32_16x16x32_bf16 v[84:87], v[8:11], v[48:51], 0
	v_mfma_f32_16x16x32_bf16 v[92:95], v[4:7], v[60:63], v[88:91]
	v_mfma_f32_16x16x32_bf16 v[88:91], v[8:11], v[56:59], 0
	v_mfma_f32_16x16x32_bf16 v[64:67], v[4:7], v[36:39], v[64:67]
	v_mfma_f32_16x16x32_bf16 v[68:71], v[12:15], v[36:39], v[68:71]
	v_mfma_f32_16x16x32_bf16 v[72:75], v[4:7], v[44:47], v[72:75]
	v_mfma_f32_16x16x32_bf16 v[76:79], v[12:15], v[44:47], v[76:79]
	v_mfma_f32_16x16x32_bf16 v[80:83], v[4:7], v[52:55], v[80:83]
	v_mfma_f32_16x16x32_bf16 v[84:87], v[12:15], v[52:55], v[84:87]
	v_mfma_f32_16x16x32_bf16 v[102:105], v[12:15], v[60:63], v[88:91]
	v_mfma_f32_16x16x32_bf16 v[88:91], v[16:19], v[32:35], 0
	v_mfma_f32_16x16x32_bf16 v[32:35], v[24:27], v[32:35], 0
	v_mfma_f32_16x16x32_bf16 v[110:113], v[20:23], v[36:39], v[88:91]
	v_mfma_f32_16x16x32_bf16 v[32:35], v[28:31], v[36:39], v[32:35]
	v_mfma_f32_16x16x32_bf16 v[36:39], v[16:19], v[40:43], 0
	v_mfma_f32_16x16x32_bf16 v[40:43], v[24:27], v[40:43], 0
	v_mfma_f32_16x16x32_bf16 v[36:39], v[20:23], v[44:47], v[36:39]
	v_mfma_f32_16x16x32_bf16 v[40:43], v[28:31], v[44:47], v[40:43]
	v_mfma_f32_16x16x32_bf16 v[44:47], v[16:19], v[48:51], 0
	v_mfma_f32_16x16x32_bf16 v[48:51], v[24:27], v[48:51], 0
	v_mfma_f32_16x16x32_bf16 v[44:47], v[20:23], v[52:55], v[44:47]
	v_mfma_f32_16x16x32_bf16 v[48:51], v[28:31], v[52:55], v[48:51]
	v_mfma_f32_16x16x32_bf16 v[52:55], v[16:19], v[56:59], 0
	v_mfma_f32_16x16x32_bf16 v[56:59], v[24:27], v[56:59], 0
	v_mfma_f32_16x16x32_bf16 v[52:55], v[20:23], v[60:63], v[52:55]
	v_mfma_f32_16x16x32_bf16 v[56:59], v[28:31], v[60:63], v[56:59]
	s_barrier
	v_lshl_add_u64 v[154:155], s[0:1], 0, v[132:133]
	s_mov_b64 s[2:3], 0x100
	s_add_i32 s61, s61, s9
	v_lshl_add_u64 v[144:145], v[154:155], 0, s[2:3]
	s_mov_b32 m0, s61
	v_lshl_add_u64 v[178:179], s[0:1], 0, v[136:137]
	s_add_i32 s96, s61, 0x2000
	ds_read_b128 v[60:63], v156 offset:16384
	ds_read_b128 v[88:91], v156 offset:17408
	ds_read_b128 v[98:101], v156 offset:18432
	ds_read_b128 v[106:109], v156 offset:19456
	ds_read_b128 v[114:117], v156 offset:20480
	ds_read_b128 v[118:121], v156 offset:21504
	ds_read_b128 v[122:125], v156 offset:22528
	ds_read_b128 v[126:129], v156 offset:23552
	global_load_lds_dwordx4 v[144:145], off
	v_lshl_add_u64 v[144:145], v[178:179], 0, s[2:3]
	s_add_u32 s2, s0, 0x40100
	s_mov_b32 m0, s96
	s_addc_u32 s3, s1, 0
	s_add_i32 s97, s97, s9
	global_load_lds_dwordx4 v[144:145], off
	s_mov_b32 m0, s97
	s_add_i32 s98, s97, 0x2000
	global_load_lds_dwordx4 v132, s[2:3]
	s_mov_b32 m0, s98
	s_nop 0
	global_load_lds_dwordx4 v136, s[2:3]
	s_mov_b32 m0, s23
	s_nop 0
	global_load_lds_dwordx4 v130, s[44:45]
	s_mov_b32 m0, s39
	s_nop 0
	global_load_lds_dwordx4 v134, s[44:45]
	s_waitcnt vmcnt(8)
	s_waitcnt lgkmcnt(0)
	s_barrier
	v_mfma_f32_16x16x32_bf16 v[144:147], v[0:3], v[60:63], 0
	v_mfma_f32_16x16x32_bf16 v[158:161], v[0:3], v[98:101], 0
	v_mfma_f32_16x16x32_bf16 v[166:169], v[0:3], v[114:117], 0
	v_mfma_f32_16x16x32_bf16 v[0:3], v[0:3], v[122:125], 0
	v_mfma_f32_16x16x32_bf16 v[146:149], v[4:7], v[88:91], v[144:147]
	v_mfma_f32_16x16x32_bf16 v[158:161], v[4:7], v[106:109], v[158:161]
	v_mfma_f32_16x16x32_bf16 v[166:169], v[4:7], v[118:121], v[166:169]
	v_mfma_f32_16x16x32_bf16 v[0:3], v[4:7], v[126:129], v[0:3]
	v_mfma_f32_16x16x32_bf16 v[4:7], v[8:11], v[122:125], 0
	v_mfma_f32_16x16x32_bf16 v[150:153], v[8:11], v[60:63], 0
	v_mfma_f32_16x16x32_bf16 v[162:165], v[8:11], v[98:101], 0
	v_mfma_f32_16x16x32_bf16 v[170:173], v[8:11], v[114:117], 0
	v_mfma_f32_16x16x32_bf16 v[4:7], v[12:15], v[126:129], v[4:7]
	v_mfma_f32_16x16x32_bf16 v[150:153], v[12:15], v[88:91], v[150:153]
	v_mfma_f32_16x16x32_bf16 v[162:165], v[12:15], v[106:109], v[162:165]
	v_mfma_f32_16x16x32_bf16 v[170:173], v[12:15], v[118:121], v[170:173]
	v_mfma_f32_16x16x32_bf16 v[8:11], v[16:19], v[60:63], 0
	v_mfma_f32_16x16x32_bf16 v[12:15], v[20:23], v[88:91], v[8:11]
	v_mfma_f32_16x16x32_bf16 v[8:11], v[24:27], v[60:63], 0
	v_mfma_f32_16x16x32_bf16 v[174:177], v[28:31], v[88:91], v[8:11]
	v_mfma_f32_16x16x32_bf16 v[8:11], v[16:19], v[98:101], 0
	v_mfma_f32_16x16x32_bf16 v[188:191], v[20:23], v[106:109], v[8:11]
	v_mfma_f32_16x16x32_bf16 v[8:11], v[24:27], v[98:101], 0
	v_mfma_f32_16x16x32_bf16 v[192:195], v[28:31], v[106:109], v[8:11]
	v_mfma_f32_16x16x32_bf16 v[8:11], v[16:19], v[114:117], 0
	v_mfma_f32_16x16x32_bf16 v[196:199], v[20:23], v[118:121], v[8:11]
	v_mfma_f32_16x16x32_bf16 v[8:11], v[24:27], v[114:117], 0
	v_mfma_f32_16x16x32_bf16 v[200:203], v[28:31], v[118:121], v[8:11]
	v_mfma_f32_16x16x32_bf16 v[8:11], v[16:19], v[122:125], 0
	v_mfma_f32_16x16x32_bf16 v[204:207], v[20:23], v[126:129], v[8:11]
	v_mfma_f32_16x16x32_bf16 v[8:11], v[24:27], v[122:125], 0
	v_mfma_f32_16x16x32_bf16 v[208:211], v[28:31], v[126:129], v[8:11]
	s_barrier
	s_add_i32 s99, 0, 0x18000
	s_add_i32 vcc_hi, 0, 0x1c000
	v_add_u32_e32 v144, s99, v97
	v_add_u32_e32 v145, vcc_hi, v97
	s_nop 0
	ds_read_b128 v[8:11], v144
	ds_read_b128 v[20:23], v144 offset:1024
	ds_read_b128 v[28:31], v144 offset:2048
	ds_read_b128 v[212:215], v144 offset:3072
	ds_read_b128 v[216:219], v145
	ds_read_b128 v[220:223], v145 offset:1024
	ds_read_b128 v[234:237], v145 offset:2048
	ds_read_b128 v[238:241], v145 offset:3072
	s_add_u32 s2, s34, 0x804000
	s_addc_u32 s3, s35, 0
	s_mov_b32 m0, s46
	ds_read_b128 v[16:19], v156 offset:32768
	ds_read_b128 v[24:27], v156 offset:33792
	ds_read_b128 v[242:245], v156 offset:34816
	ds_read_b128 v[246:249], v156 offset:35840
	ds_read_b128 v[228:231], v156 offset:36864
	ds_read_b128 v[180:183], v156 offset:37888
	ds_read_b128 v[184:187], v156 offset:38912
	ds_read_b128 v[224:227], v156 offset:39936
	global_load_lds_dwordx4 v130, s[2:3]
	s_mov_b32 m0, s47
	s_nop 0
	global_load_lds_dwordx4 v134, s[2:3]
	s_waitcnt vmcnt(8)
	s_waitcnt lgkmcnt(0)
	s_barrier
	v_mfma_f32_16x16x32_bf16 v[60:63], v[8:11], v[16:19], v[64:67]
	v_mfma_f32_16x16x32_bf16 v[122:125], v[20:23], v[24:27], v[60:63]
	v_mfma_f32_16x16x32_bf16 v[60:63], v[28:31], v[16:19], v[68:71]
	v_mfma_f32_16x16x32_bf16 v[114:117], v[212:215], v[24:27], v[60:63]
	v_mfma_f32_16x16x32_bf16 v[60:63], v[8:11], v[242:245], v[72:75]
	v_mfma_f32_16x16x32_bf16 v[106:109], v[20:23], v[246:249], v[60:63]
	v_mfma_f32_16x16x32_bf16 v[60:63], v[28:31], v[242:245], v[76:79]
	v_mfma_f32_16x16x32_bf16 v[98:101], v[212:215], v[246:249], v[60:63]
	v_mfma_f32_16x16x32_bf16 v[60:63], v[8:11], v[228:231], v[80:83]
	v_mfma_f32_16x16x32_bf16 v[88:91], v[20:23], v[180:183], v[60:63]
	v_mfma_f32_16x16x32_bf16 v[60:63], v[28:31], v[228:231], v[84:87]
	v_mfma_f32_16x16x32_bf16 v[80:83], v[212:215], v[180:183], v[60:63]
	v_mfma_f32_16x16x32_bf16 v[60:63], v[8:11], v[184:187], v[92:95]
	v_mfma_f32_16x16x32_bf16 v[72:75], v[20:23], v[224:227], v[60:63]
	v_mfma_f32_16x16x32_bf16 v[60:63], v[28:31], v[184:187], v[102:105]
	v_mfma_f32_16x16x32_bf16 v[60:63], v[212:215], v[224:227], v[60:63]
	v_mfma_f32_16x16x32_bf16 v[64:67], v[216:219], v[16:19], v[110:113]
	v_mfma_f32_16x16x32_bf16 v[16:19], v[234:237], v[16:19], v[32:35]
	v_mfma_f32_16x16x32_bf16 v[118:121], v[238:241], v[24:27], v[16:19]
	v_mfma_f32_16x16x32_bf16 v[16:19], v[216:219], v[242:245], v[36:39]
	v_mfma_f32_16x16x32_bf16 v[110:113], v[220:223], v[246:249], v[16:19]
	v_mfma_f32_16x16x32_bf16 v[16:19], v[234:237], v[242:245], v[40:43]
	v_mfma_f32_16x16x32_bf16 v[102:105], v[238:241], v[246:249], v[16:19]
	v_mfma_f32_16x16x32_bf16 v[16:19], v[216:219], v[228:231], v[44:47]
	v_mfma_f32_16x16x32_bf16 v[92:95], v[220:223], v[180:183], v[16:19]
	v_mfma_f32_16x16x32_bf16 v[16:19], v[234:237], v[228:231], v[48:51]
	v_mfma_f32_16x16x32_bf16 v[84:87], v[238:241], v[180:183], v[16:19]
	v_mfma_f32_16x16x32_bf16 v[16:19], v[216:219], v[184:187], v[52:55]
	v_mfma_f32_16x16x32_bf16 v[76:79], v[220:223], v[224:227], v[16:19]
	v_mfma_f32_16x16x32_bf16 v[16:19], v[234:237], v[184:187], v[56:59]
	v_mfma_f32_16x16x32_bf16 v[126:129], v[220:223], v[24:27], v[64:67]
	v_mfma_f32_16x16x32_bf16 v[68:71], v[238:241], v[224:227], v[16:19]
	s_barrier
; template <class Epi, class Sched, bool ALIGN_EPI = false, bool SP2 = false>
; __device__ __forceinline__ void gemm_phase(PG8_LAS unsigned char* lds, const Gemm g, const Sched& S, const Epi& E) {
;     ...
;         if constexpr (Epi::PEEL) {
;             const char* a1 = cA + kstepA; const char* a2 = cA + 2 * kstepA; const char* b2 = cB + 2 * kstepB; const char* a3 = a2 + kstepA; const char* b3 = b2 + kstepB;
;             PG8_ITER(8);
;         }
;         for (int t = (Epi::PEEL ? 2 : 0); t < nt; t += 2) {
;             const bool last = (t == nt - 2);
;             const char* a1 = cA + (size_t)(t + 1) * kstepA;
;             const char* a2 = last ? nA : cA + (size_t)(t + 2) * kstepA; const char* b2 = last ? nB : cB + (size_t)(t + 2) * kstepB;
;             const char* a3 = a2 + kstepA; const char* b3 = b2 + kstepB;
	s_mov_b64 s[2:3], 0x180
	s_add_i32 s99, s99, s9
	s_nop 1
	v_lshl_add_u64 v[16:17], v[154:155], 0, s[2:3]
	s_mov_b32 m0, s99
	s_add_i32 vcc_lo, s99, 0x2000
	ds_read_b128 v[36:39], v156 offset:49152
	ds_read_b128 v[44:47], v156 offset:50176
	ds_read_b128 v[180:183], v156 offset:51200
	ds_read_b128 v[184:187], v156 offset:52224
	ds_read_b128 v[224:227], v156 offset:53248
	ds_read_b128 v[228:231], v156 offset:54272
	ds_read_b128 v[242:245], v156 offset:55296
	ds_read_b128 v[246:249], v156 offset:56320
	global_load_lds_dwordx4 v[16:17], off
	v_lshl_add_u64 v[16:17], v[178:179], 0, s[2:3]
	s_add_u32 s2, s0, 0x40180
	s_mov_b32 m0, vcc_lo
	s_addc_u32 s3, s1, 0
	s_add_i32 vcc_hi, vcc_hi, s9
	global_load_lds_dwordx4 v[16:17], off
	s_mov_b32 m0, vcc_hi
	s_add_i32 s38, vcc_hi, 0x2000
	global_load_lds_dwordx4 v132, s[2:3]
	s_mov_b32 m0, s38
	s_nop 0
	global_load_lds_dwordx4 v136, s[2:3]
	s_mov_b32 m0, s49
	s_nop 0
	global_load_lds_dwordx4 v130, s[42:43]
	s_mov_b32 m0, s50
	s_nop 0
	global_load_lds_dwordx4 v134, s[42:43]
	s_waitcnt vmcnt(8)
	s_waitcnt lgkmcnt(0)
	s_barrier
	v_mfma_f32_16x16x32_bf16 v[16:19], v[8:11], v[36:39], v[146:149]
	v_mfma_f32_16x16x32_bf16 v[56:59], v[20:23], v[44:47], v[16:19]
	v_mfma_f32_16x16x32_bf16 v[16:19], v[28:31], v[36:39], v[150:153]
	v_mfma_f32_16x16x32_bf16 v[48:51], v[212:215], v[44:47], v[16:19]
	v_mfma_f32_16x16x32_bf16 v[16:19], v[8:11], v[180:183], v[158:161]
	v_mfma_f32_16x16x32_bf16 v[40:43], v[20:23], v[184:187], v[16:19]
	v_mfma_f32_16x16x32_bf16 v[16:19], v[28:31], v[180:183], v[162:165]
	v_mfma_f32_16x16x32_bf16 v[32:35], v[212:215], v[184:187], v[16:19]
	v_mfma_f32_16x16x32_bf16 v[16:19], v[8:11], v[224:227], v[166:169]
	v_mfma_f32_16x16x32_bf16 v[0:3], v[8:11], v[242:245], v[0:3]
	v_mfma_f32_16x16x32_bf16 v[24:27], v[20:23], v[228:231], v[16:19]
	v_mfma_f32_16x16x32_bf16 v[16:19], v[28:31], v[224:227], v[170:173]
	v_mfma_f32_16x16x32_bf16 v[8:11], v[20:23], v[246:249], v[0:3]
	v_mfma_f32_16x16x32_bf16 v[0:3], v[28:31], v[242:245], v[4:7]
	v_mfma_f32_16x16x32_bf16 v[16:19], v[212:215], v[228:231], v[16:19]
	v_mfma_f32_16x16x32_bf16 v[0:3], v[212:215], v[246:249], v[0:3]
	v_mfma_f32_16x16x32_bf16 v[4:7], v[216:219], v[36:39], v[12:15]
	v_mfma_f32_16x16x32_bf16 v[64:67], v[220:223], v[44:47], v[4:7]
	v_mfma_f32_16x16x32_bf16 v[4:7], v[234:237], v[36:39], v[174:177]
	v_mfma_f32_16x16x32_bf16 v[52:55], v[238:241], v[44:47], v[4:7]
	v_mfma_f32_16x16x32_bf16 v[4:7], v[216:219], v[180:183], v[188:191]
	v_mfma_f32_16x16x32_bf16 v[44:47], v[220:223], v[184:187], v[4:7]
	v_mfma_f32_16x16x32_bf16 v[4:7], v[234:237], v[180:183], v[192:195]
	v_mfma_f32_16x16x32_bf16 v[36:39], v[238:241], v[184:187], v[4:7]
	v_mfma_f32_16x16x32_bf16 v[4:7], v[216:219], v[224:227], v[196:199]
	v_mfma_f32_16x16x32_bf16 v[28:31], v[220:223], v[228:231], v[4:7]
	v_mfma_f32_16x16x32_bf16 v[4:7], v[234:237], v[224:227], v[200:203]
	v_mfma_f32_16x16x32_bf16 v[20:23], v[238:241], v[228:231], v[4:7]
	v_mfma_f32_16x16x32_bf16 v[4:7], v[216:219], v[242:245], v[204:207]
	v_mfma_f32_16x16x32_bf16 v[12:15], v[220:223], v[246:249], v[4:7]
	v_mfma_f32_16x16x32_bf16 v[4:7], v[234:237], v[242:245], v[208:211]
	v_mfma_f32_16x16x32_bf16 v[4:7], v[238:241], v[246:249], v[4:7]
	s_barrier
	s_add_u32 s3, s0, 0x200
	s_addc_u32 s2, s1, 0
	s_add_u32 s0, s34, 0xc04000
	s_addc_u32 s1, s35, 0
	s_mov_b32 s18, 0

;     __device__ __forceinline__ void operator()(const f32x4 (&acc)[2][2][4][2], const Unit& u, int wr, int wc, int fr, int fq, const LAS float* rt) const {
;         const int row0 = u.pm * 256 + wr * 64 + fr;
;         bf16_t* Ob = O + (size_t)(2 * u.pn + (wc >> 1)) * M * 64 + (wc & 1) * 32 + 8 * fq;
;         float rsv[2][4];
; #pragma unroll
;         for (int ai = 0; ai < 2; ++ai)
; #pragma unroll
;             for (int m = 0; m < 4; ++m) rsv[ai][m] = rt ? rt[wr * 64 + fr + ai * 128 + m * 16] : row_rstd(ssq, row0 + ai * 128 + m * 16);
.LBB0_487:
	v_cndmask_b32_e64 v142, 0, 1, s[34:35]
	v_cmp_ne_u32_e64 s[0:1], 1, v142
	s_andn2_b64 vcc, exec, s[34:35]
	s_mov_b64 s[34:35], -1
	s_cbranch_vccnz .LBB0_499
	ds_read_b32 v163, v145 offset:64
	v_or_b32_e32 v152, 16, v154
	v_ashrrev_i32_e32 v153, 31, v152
	ds_read_b32 v162, v145 offset:128
	v_or_b32_e32 v150, 32, v154
	v_ashrrev_i32_e32 v151, 31, v150
	ds_read_b32 v161, v145 offset:192
	v_or_b32_e32 v148, 48, v154
	v_ashrrev_i32_e32 v149, 31, v148
	ds_read_b32 v160, v145 offset:512
	v_add_u32_e32 v146, 0x80, v154
	v_ashrrev_i32_e32 v147, 31, v146
	ds_read_b32 v159, v145 offset:576
	ds_read_b32 v158, v145 offset:640
	v_add_u32_e32 v142, 0xb0, v154
	v_ashrrev_i32_e32 v143, 31, v142
	ds_read_b32 v157, v145 offset:704
	s_mov_b64 s[34:35], 0
	s_mov_b64 vcc, exec
	s_branch .LBB0_515
